# GEMM K-loop: per-phase s_setprio flips removed (A/B)
# speedup vs baseline: 1.0144x; 1.0144x over previous
; #define PG8_STAGE(bufoff, gbase, voff) do { _Pragma("unroll") for (int _i = 0; _i < 2; ++_i) \
;     __builtin_amdgcn_global_load_lds((const unsigned*)((const char*)(gbase) + (voff)[_i]), (LAS unsigned*)(lds + (bufoff) + ldsw + _i * 8192), 16, 0, 0); } while (0)
; #define PG8_LDA(dst, b, h) do { _Pragma("unroll") for (int m = 0; m < 4; ++m) _Pragma("unroll") for (int k = 0; k < 2; ++k) dst[m][k] = *(const LAS bf16x8*)(lds + PG8_SA(b, h) + aoff + m * 2048 + k * 1024); } while (0)
; #define PG8_LDB(dst, b, h) do { _Pragma("unroll") for (int n = 0; n < 2; ++n) _Pragma("unroll") for (int k = 0; k < 2; ++k) dst[n][k] = *(const LAS bf16x8*)(lds + PG8_SB(b, h) + boff + n * 2048 + k * 1024); } while (0)
; #define PG8_MMA(ai, bj, At, Bt) do { __builtin_amdgcn_s_setprio(1); _Pragma("unroll") for (int m = 0; m < 4; ++m) _Pragma("unroll") for (int n = 0; n < 2; ++n) _Pragma("unroll") for (int k = 0; k < 2; ++k) \
;     acc[ai][bj][m][n] = __builtin_amdgcn_mfma_f32_16x16x32_bf16(Bt[n][k], At[m][k], acc[ai][bj][m][n], 0, 0, 0); __builtin_amdgcn_s_setprio(0); } while (0)
; #define PG8_WAIT_V(n) asm volatile("s_waitcnt vmcnt(" #n ")" ::: "memory")
; #define PG8_WAIT_L(n) asm volatile("s_waitcnt lgkmcnt(" #n ")" ::: "memory")
; #define PG8_BAR __builtin_amdgcn_s_barrier()
; #define PG8_SCHED __builtin_amdgcn_sched_barrier(0)
; template <class Epi>
; __device__ __forceinline__ void gemm_phase(LAS unsigned char* lds, const Gemm g, const StaticOrder& S, const Epi& E) {
;     ...
;       PG8_LDB(B0, 0, 0); PG8_SCHED; PG8_LDA(At, 0, 0); PG8_STAGE(PG8_SA(1, 1), a1 + hstep, voffA);
;       PG8_WAIT_L(8); PG8_BAR; PG8_WAIT_L(0); PG8_MMA(0, 0, At, B0); PG8_BAR; PG8_SCHED;
;       PG8_LDB(B1, 0, 1); PG8_STAGE(PG8_SB(0, 0), b2, voffB);
;       PG8_BAR; PG8_WAIT_L(0); PG8_MMA(0, 1, At, B1); PG8_BAR;
;       PG8_LDA(At, 0, 1); PG8_STAGE(PG8_SA(0, 0), a2, voffA);
;       PG8_BAR; PG8_WAIT_L(0); PG8_MMA(1, 0, At, B0); PG8_BAR; PG8_SCHED;
;       PG8_STAGE(PG8_SB(0, 1), b2 + hstep, voffB);
;       PG8_WAIT_V(6); PG8_BAR; PG8_MMA(1, 1, At, B1); PG8_BAR;
.LBB0_56:
	s_add_i32 s76, s10, 2
	s_add_u32 s12, s0, 0x80
	s_addc_u32 s11, s1, 0
	s_add_i32 s77, 0, 0x10000
	s_waitcnt lgkmcnt(0)
	v_add_u32_e32 v80, s77, v187
	ds_read_b128 v[130:133], v80
	ds_read_b128 v[134:137], v80 offset:1024
	ds_read_b128 v[138:141], v80 offset:2048
	ds_read_b128 v[142:145], v80 offset:3072
	s_cmp_eq_u32 s21, s10
	s_cselect_b32 s10, s18, s12
	s_cselect_b32 s11, s19, s11
	s_cselect_b32 s13, s17, s75
	s_cselect_b32 s12, s16, s74
	v_lshl_add_u64 v[194:195], s[0:1], 0, v[172:173]
	s_add_i32 m0, s15, 0xc000
	ds_read_b128 v[146:149], v189
	ds_read_b128 v[150:153], v189 offset:1024
	ds_read_b128 v[154:157], v189 offset:2048
	ds_read_b128 v[158:161], v189 offset:3072
	ds_read_b128 v[174:177], v189 offset:4096
	ds_read_b128 v[178:181], v189 offset:5120
	ds_read_b128 v[182:185], v189 offset:6144
	ds_read_b128 v[190:193], v189 offset:7168
	global_load_lds_dwordx4 v[194:195], off
	v_lshl_add_u64 v[194:195], s[0:1], 0, v[170:171]
	s_add_i32 m0, s15, 0xe000
	s_nop 0
	global_load_lds_dwordx4 v[194:195], off
	s_waitcnt lgkmcnt(8)
	s_barrier
	s_waitcnt lgkmcnt(0)
	s_waitcnt lgkmcnt(0)
	v_mfma_f32_16x16x32_bf16 v[126:129], v[130:133], v[146:149], v[126:129]
	v_mfma_f32_16x16x32_bf16 v[122:125], v[138:141], v[146:149], v[122:125]
	v_mfma_f32_16x16x32_bf16 v[118:121], v[130:133], v[154:157], v[118:121]
	v_mfma_f32_16x16x32_bf16 v[114:117], v[138:141], v[154:157], v[114:117]
	v_mfma_f32_16x16x32_bf16 v[110:113], v[130:133], v[174:177], v[110:113]
	v_mfma_f32_16x16x32_bf16 v[106:109], v[138:141], v[174:177], v[106:109]
	v_mfma_f32_16x16x32_bf16 v[102:105], v[130:133], v[182:185], v[102:105]
	v_mfma_f32_16x16x32_bf16 v[98:101], v[138:141], v[182:185], v[98:101]
	v_mfma_f32_16x16x32_bf16 v[126:129], v[134:137], v[150:153], v[126:129]
	v_mfma_f32_16x16x32_bf16 v[122:125], v[142:145], v[150:153], v[122:125]
	v_mfma_f32_16x16x32_bf16 v[118:121], v[134:137], v[158:161], v[118:121]
	v_mfma_f32_16x16x32_bf16 v[114:117], v[142:145], v[158:161], v[114:117]
	v_mfma_f32_16x16x32_bf16 v[110:113], v[134:137], v[178:181], v[110:113]
	v_mfma_f32_16x16x32_bf16 v[106:109], v[142:145], v[178:181], v[106:109]
	v_mfma_f32_16x16x32_bf16 v[102:105], v[134:137], v[190:193], v[102:105]
	v_mfma_f32_16x16x32_bf16 v[98:101], v[142:145], v[190:193], v[98:101]
	s_barrier
	s_add_i32 s78, 0, 0x14000
	s_add_i32 s77, s77, s14
	v_add_u32_e32 v80, s78, v187
	v_lshl_add_u64 v[210:211], s[12:13], 0, v[164:165]
	s_mov_b32 m0, s77
	ds_read_b128 v[194:197], v80
	ds_read_b128 v[198:201], v80 offset:1024
	ds_read_b128 v[202:205], v80 offset:2048
	ds_read_b128 v[206:209], v80 offset:3072
	global_load_lds_dwordx4 v[210:211], off
	v_lshl_add_u64 v[212:213], s[12:13], 0, v[168:169]
	s_add_i32 m0, s77, 0x2000
	s_nop 0
	global_load_lds_dwordx4 v[212:213], off
	s_barrier
	s_waitcnt lgkmcnt(0)
	s_waitcnt lgkmcnt(0)
	v_mfma_f32_16x16x32_bf16 v[60:63], v[194:197], v[146:149], v[60:63]
	v_mfma_f32_16x16x32_bf16 v[56:59], v[202:205], v[146:149], v[56:59]
	v_mfma_f32_16x16x32_bf16 v[52:55], v[194:197], v[154:157], v[52:55]
	v_mfma_f32_16x16x32_bf16 v[48:51], v[202:205], v[154:157], v[48:51]
	v_mfma_f32_16x16x32_bf16 v[44:47], v[194:197], v[174:177], v[44:47]
	v_mfma_f32_16x16x32_bf16 v[40:43], v[202:205], v[174:177], v[40:43]
	v_mfma_f32_16x16x32_bf16 v[36:39], v[194:197], v[182:185], v[36:39]
	v_mfma_f32_16x16x32_bf16 v[32:35], v[202:205], v[182:185], v[32:35]
	v_mfma_f32_16x16x32_bf16 v[60:63], v[198:201], v[150:153], v[60:63]
	v_mfma_f32_16x16x32_bf16 v[56:59], v[206:209], v[150:153], v[56:59]
	v_mfma_f32_16x16x32_bf16 v[52:55], v[198:201], v[158:161], v[52:55]
	v_mfma_f32_16x16x32_bf16 v[48:51], v[206:209], v[158:161], v[48:51]
	v_mfma_f32_16x16x32_bf16 v[44:47], v[198:201], v[178:181], v[44:47]
	v_mfma_f32_16x16x32_bf16 v[40:43], v[206:209], v[178:181], v[40:43]
	v_mfma_f32_16x16x32_bf16 v[36:39], v[198:201], v[190:193], v[36:39]
	v_mfma_f32_16x16x32_bf16 v[32:35], v[206:209], v[190:193], v[32:35]
	s_mov_b32 m0, s15
	v_lshl_add_u64 v[216:217], s[10:11], 0, v[162:163]
	s_barrier
	ds_read_b128 v[146:149], v189 offset:16384
	ds_read_b128 v[150:153], v189 offset:17408
	ds_read_b128 v[154:157], v189 offset:18432
	ds_read_b128 v[158:161], v189 offset:19456
	ds_read_b128 v[174:177], v189 offset:20480
	ds_read_b128 v[178:181], v189 offset:21504
	ds_read_b128 v[182:185], v189 offset:22528
	ds_read_b128 v[190:193], v189 offset:23552
	global_load_lds_dwordx4 v[216:217], off
	v_lshl_add_u64 v[232:233], s[10:11], 0, v[166:167]
	s_mov_b32 m0, s84
	s_nop 0
	global_load_lds_dwordx4 v[232:233], off
	s_barrier
	s_waitcnt lgkmcnt(0)
	s_waitcnt lgkmcnt(0)
	v_mfma_f32_16x16x32_bf16 v[94:97], v[130:133], v[146:149], v[94:97]
	v_mfma_f32_16x16x32_bf16 v[90:93], v[138:141], v[146:149], v[90:93]
	v_mfma_f32_16x16x32_bf16 v[86:89], v[130:133], v[154:157], v[86:89]
	v_mfma_f32_16x16x32_bf16 v[82:85], v[138:141], v[154:157], v[82:85]
	v_mfma_f32_16x16x32_bf16 v[76:79], v[130:133], v[174:177], v[76:79]
	v_mfma_f32_16x16x32_bf16 v[72:75], v[138:141], v[174:177], v[72:75]
	v_mfma_f32_16x16x32_bf16 v[68:71], v[130:133], v[182:185], v[68:71]
	v_mfma_f32_16x16x32_bf16 v[64:67], v[138:141], v[182:185], v[64:67]
	v_mfma_f32_16x16x32_bf16 v[94:97], v[134:137], v[150:153], v[94:97]
	v_mfma_f32_16x16x32_bf16 v[90:93], v[142:145], v[150:153], v[90:93]
	v_mfma_f32_16x16x32_bf16 v[86:89], v[134:137], v[158:161], v[86:89]
	v_mfma_f32_16x16x32_bf16 v[82:85], v[142:145], v[158:161], v[82:85]
	v_mfma_f32_16x16x32_bf16 v[76:79], v[134:137], v[178:181], v[76:79]
	v_mfma_f32_16x16x32_bf16 v[72:75], v[142:145], v[178:181], v[72:75]
	v_mfma_f32_16x16x32_bf16 v[68:71], v[134:137], v[190:193], v[68:71]
	v_mfma_f32_16x16x32_bf16 v[64:67], v[142:145], v[190:193], v[64:67]
	s_barrier
; #define PG8_STAGE(bufoff, gbase, voff) do { _Pragma("unroll") for (int _i = 0; _i < 2; ++_i) \
;     __builtin_amdgcn_global_load_lds((const unsigned*)((const char*)(gbase) + (voff)[_i]), (LAS unsigned*)(lds + (bufoff) + ldsw + _i * 8192), 16, 0, 0); } while (0)
; #define PG8_LDA(dst, b, h) do { _Pragma("unroll") for (int m = 0; m < 4; ++m) _Pragma("unroll") for (int k = 0; k < 2; ++k) dst[m][k] = *(const LAS bf16x8*)(lds + PG8_SA(b, h) + aoff + m * 2048 + k * 1024); } while (0)
; #define PG8_LDB(dst, b, h) do { _Pragma("unroll") for (int n = 0; n < 2; ++n) _Pragma("unroll") for (int k = 0; k < 2; ++k) dst[n][k] = *(const LAS bf16x8*)(lds + PG8_SB(b, h) + boff + n * 2048 + k * 1024); } while (0)
; #define PG8_MMA(ai, bj, At, Bt) do { __builtin_amdgcn_s_setprio(1); _Pragma("unroll") for (int m = 0; m < 4; ++m) _Pragma("unroll") for (int n = 0; n < 2; ++n) _Pragma("unroll") for (int k = 0; k < 2; ++k) \
;     acc[ai][bj][m][n] = __builtin_amdgcn_mfma_f32_16x16x32_bf16(Bt[n][k], At[m][k], acc[ai][bj][m][n], 0, 0, 0); __builtin_amdgcn_s_setprio(0); } while (0)
; #define PG8_WAIT_V(n) asm volatile("s_waitcnt vmcnt(" #n ")" ::: "memory")
; #define PG8_WAIT_L(n) asm volatile("s_waitcnt lgkmcnt(" #n ")" ::: "memory")
; #define PG8_BAR __builtin_amdgcn_s_barrier()
; #define PG8_SCHED __builtin_amdgcn_sched_barrier(0)
; template <class Epi>
; __device__ __forceinline__ void gemm_phase(LAS unsigned char* lds, const Gemm g, const StaticOrder& S, const Epi& E) {
;     ...
;       PG8_WAIT_V(6); PG8_BAR; PG8_MMA(1, 1, At, B1); PG8_BAR;
;       PG8_LDB(B0, 1, 0); PG8_SCHED; PG8_LDA(At, 1, 0); PG8_STAGE(PG8_SA(0, 1), a2 + hstep, voffA);
;       PG8_WAIT_L(8); PG8_BAR; PG8_WAIT_L(0); PG8_MMA(0, 0, At, B0); PG8_BAR; PG8_SCHED;
;       PG8_LDB(B1, 1, 1); PG8_STAGE(PG8_SB(1, 0), b3, voffB);
;       PG8_BAR; PG8_WAIT_L(0); PG8_MMA(0, 1, At, B1); PG8_BAR;
;       PG8_LDA(At, 1, 1); PG8_STAGE(PG8_SA(1, 0), a3, voffA);
;       PG8_BAR; PG8_WAIT_L(0); PG8_MMA(1, 0, At, B0); PG8_BAR; PG8_SCHED;
	s_add_u32 s12, s12, s64
	s_addc_u32 s13, s13, 0
	s_add_i32 s77, s78, s14
	v_lshl_add_u64 v[236:237], s[12:13], 0, v[164:165]
	s_mov_b32 m0, s77
	v_lshl_add_u64 v[242:243], s[12:13], 0, v[168:169]
	global_load_lds_dwordx4 v[236:237], off
	s_add_i32 m0, s77, 0x2000
	s_nop 0
	global_load_lds_dwordx4 v[242:243], off
	s_waitcnt vmcnt(6)
	s_barrier
	v_mfma_f32_16x16x32_bf16 v[28:31], v[194:197], v[146:149], v[28:31]
	v_mfma_f32_16x16x32_bf16 v[24:27], v[202:205], v[146:149], v[24:27]
	v_mfma_f32_16x16x32_bf16 v[20:23], v[194:197], v[154:157], v[20:23]
	v_mfma_f32_16x16x32_bf16 v[16:19], v[202:205], v[154:157], v[16:19]
	v_mfma_f32_16x16x32_bf16 v[12:15], v[194:197], v[174:177], v[12:15]
	v_mfma_f32_16x16x32_bf16 v[8:11], v[202:205], v[174:177], v[8:11]
	v_mfma_f32_16x16x32_bf16 v[4:7], v[194:197], v[182:185], v[4:7]
	v_mfma_f32_16x16x32_bf16 v[0:3], v[202:205], v[182:185], v[0:3]
	v_mfma_f32_16x16x32_bf16 v[28:31], v[198:201], v[150:153], v[28:31]
	v_mfma_f32_16x16x32_bf16 v[24:27], v[206:209], v[150:153], v[24:27]
	v_mfma_f32_16x16x32_bf16 v[20:23], v[198:201], v[158:161], v[20:23]
	v_mfma_f32_16x16x32_bf16 v[16:19], v[206:209], v[158:161], v[16:19]
	v_mfma_f32_16x16x32_bf16 v[12:15], v[198:201], v[178:181], v[12:15]
	v_mfma_f32_16x16x32_bf16 v[8:11], v[206:209], v[178:181], v[8:11]
	v_mfma_f32_16x16x32_bf16 v[4:7], v[198:201], v[190:193], v[4:7]
	v_mfma_f32_16x16x32_bf16 v[0:3], v[206:209], v[190:193], v[0:3]
	s_add_i32 s12, 0, 0x18000
	v_add_u32_e32 v80, s12, v187
	s_barrier
	ds_read_b128 v[130:133], v80
	ds_read_b128 v[134:137], v80 offset:1024
	ds_read_b128 v[138:141], v80 offset:2048
	ds_read_b128 v[142:145], v80 offset:3072
	s_add_u32 s10, s10, s64
	s_addc_u32 s11, s11, 0
	s_mov_b32 m0, s99
	v_lshl_add_u64 v[194:195], s[10:11], 0, v[162:163]
	ds_read_b128 v[146:149], v189 offset:32768
	ds_read_b128 v[150:153], v189 offset:33792
	ds_read_b128 v[154:157], v189 offset:34816
	ds_read_b128 v[158:161], v189 offset:35840
	ds_read_b128 v[174:177], v189 offset:36864
	ds_read_b128 v[178:181], v189 offset:37888
	ds_read_b128 v[182:185], v189 offset:38912
	ds_read_b128 v[190:193], v189 offset:39936
	global_load_lds_dwordx4 v[194:195], off
	v_lshl_add_u64 v[194:195], s[10:11], 0, v[166:167]
	s_mov_b32 m0, s33
	s_nop 0
	global_load_lds_dwordx4 v[194:195], off
	s_waitcnt lgkmcnt(8)
	s_barrier
	s_waitcnt lgkmcnt(0)
	s_waitcnt lgkmcnt(0)
	v_mfma_f32_16x16x32_bf16 v[126:129], v[130:133], v[146:149], v[126:129]
	v_mfma_f32_16x16x32_bf16 v[122:125], v[138:141], v[146:149], v[122:125]
	v_mfma_f32_16x16x32_bf16 v[118:121], v[130:133], v[154:157], v[118:121]
	v_mfma_f32_16x16x32_bf16 v[114:117], v[138:141], v[154:157], v[114:117]
	v_mfma_f32_16x16x32_bf16 v[110:113], v[130:133], v[174:177], v[110:113]
	v_mfma_f32_16x16x32_bf16 v[106:109], v[138:141], v[174:177], v[106:109]
	v_mfma_f32_16x16x32_bf16 v[102:105], v[130:133], v[182:185], v[102:105]
	v_mfma_f32_16x16x32_bf16 v[98:101], v[138:141], v[182:185], v[98:101]
	v_mfma_f32_16x16x32_bf16 v[126:129], v[134:137], v[150:153], v[126:129]
	v_mfma_f32_16x16x32_bf16 v[122:125], v[142:145], v[150:153], v[122:125]
	v_mfma_f32_16x16x32_bf16 v[118:121], v[134:137], v[158:161], v[118:121]
	v_mfma_f32_16x16x32_bf16 v[114:117], v[142:145], v[158:161], v[114:117]
	v_mfma_f32_16x16x32_bf16 v[110:113], v[134:137], v[178:181], v[110:113]
	v_mfma_f32_16x16x32_bf16 v[106:109], v[142:145], v[178:181], v[106:109]
	v_mfma_f32_16x16x32_bf16 v[102:105], v[134:137], v[190:193], v[102:105]
	v_mfma_f32_16x16x32_bf16 v[98:101], v[142:145], v[190:193], v[98:101]
	s_barrier
	s_add_i32 s10, 0, 0x1c000
	s_add_i32 s11, s12, s14
	v_add_u32_e32 v80, s10, v187
	v_lshl_add_u64 v[210:211], v[210:211], 0, s[90:91]
	s_mov_b32 m0, s11
	ds_read_b128 v[194:197], v80
	ds_read_b128 v[198:201], v80 offset:1024
	ds_read_b128 v[202:205], v80 offset:2048
	ds_read_b128 v[206:209], v80 offset:3072
	global_load_lds_dwordx4 v[210:211], off
	v_lshl_add_u64 v[210:211], v[212:213], 0, s[90:91]
	s_add_i32 m0, s11, 0x2000
	s_nop 0
	global_load_lds_dwordx4 v[210:211], off
	s_barrier
	s_waitcnt lgkmcnt(0)
	s_waitcnt lgkmcnt(0)
	v_mfma_f32_16x16x32_bf16 v[60:63], v[194:197], v[146:149], v[60:63]
	v_mfma_f32_16x16x32_bf16 v[56:59], v[202:205], v[146:149], v[56:59]
	v_mfma_f32_16x16x32_bf16 v[52:55], v[194:197], v[154:157], v[52:55]
	v_mfma_f32_16x16x32_bf16 v[48:51], v[202:205], v[154:157], v[48:51]
	v_mfma_f32_16x16x32_bf16 v[44:47], v[194:197], v[174:177], v[44:47]
	v_mfma_f32_16x16x32_bf16 v[40:43], v[202:205], v[174:177], v[40:43]
	v_mfma_f32_16x16x32_bf16 v[36:39], v[194:197], v[182:185], v[36:39]
	v_mfma_f32_16x16x32_bf16 v[32:35], v[202:205], v[182:185], v[32:35]
	v_mfma_f32_16x16x32_bf16 v[60:63], v[198:201], v[150:153], v[60:63]
	v_mfma_f32_16x16x32_bf16 v[56:59], v[206:209], v[150:153], v[56:59]
	v_mfma_f32_16x16x32_bf16 v[52:55], v[198:201], v[158:161], v[52:55]
	v_mfma_f32_16x16x32_bf16 v[48:51], v[206:209], v[158:161], v[48:51]
	v_mfma_f32_16x16x32_bf16 v[44:47], v[198:201], v[178:181], v[44:47]
	v_mfma_f32_16x16x32_bf16 v[40:43], v[206:209], v[178:181], v[40:43]
	v_mfma_f32_16x16x32_bf16 v[36:39], v[198:201], v[190:193], v[36:39]
	v_mfma_f32_16x16x32_bf16 v[32:35], v[206:209], v[190:193], v[32:35]
	s_mov_b32 m0, s29
	v_lshl_add_u64 v[210:211], v[216:217], 0, s[90:91]
	s_barrier
	ds_read_b128 v[146:149], v189 offset:49152
	ds_read_b128 v[150:153], v189 offset:50176
	ds_read_b128 v[154:157], v189 offset:51200
	ds_read_b128 v[158:161], v189 offset:52224
	ds_read_b128 v[174:177], v189 offset:53248
	ds_read_b128 v[178:181], v189 offset:54272
	ds_read_b128 v[182:185], v189 offset:55296
	ds_read_b128 v[190:193], v189 offset:56320
	global_load_lds_dwordx4 v[210:211], off
	v_lshl_add_u64 v[210:211], v[232:233], 0, s[90:91]
	s_mov_b32 m0, s20
	s_nop 0
	global_load_lds_dwordx4 v[210:211], off
	s_barrier
; #define PG8_STAGE(bufoff, gbase, voff) do { _Pragma("unroll") for (int _i = 0; _i < 2; ++_i) \
;     __builtin_amdgcn_global_load_lds((const unsigned*)((const char*)(gbase) + (voff)[_i]), (LAS unsigned*)(lds + (bufoff) + ldsw + _i * 8192), 16, 0, 0); } while (0)
; #define PG8_MMA(ai, bj, At, Bt) do { __builtin_amdgcn_s_setprio(1); _Pragma("unroll") for (int m = 0; m < 4; ++m) _Pragma("unroll") for (int n = 0; n < 2; ++n) _Pragma("unroll") for (int k = 0; k < 2; ++k) \
;     acc[ai][bj][m][n] = __builtin_amdgcn_mfma_f32_16x16x32_bf16(Bt[n][k], At[m][k], acc[ai][bj][m][n], 0, 0, 0); __builtin_amdgcn_s_setprio(0); } while (0)
; #define PG8_WAIT_V(n) asm volatile("s_waitcnt vmcnt(" #n ")" ::: "memory")
; #define PG8_WAIT_L(n) asm volatile("s_waitcnt lgkmcnt(" #n ")" ::: "memory")
; #define PG8_BAR __builtin_amdgcn_s_barrier()
; #define PG8_SCHED __builtin_amdgcn_sched_barrier(0)
; template <class Epi>
; __device__ __forceinline__ void gemm_phase(LAS unsigned char* lds, const Gemm g, const StaticOrder& S, const Epi& E) {
;     ...
;       PG8_BAR; PG8_WAIT_L(0); PG8_MMA(1, 0, At, B0); PG8_BAR; PG8_SCHED;
;       PG8_STAGE(PG8_SB(1, 1), b3 + hstep, voffB);
;       PG8_WAIT_V(6); PG8_BAR; PG8_MMA(1, 1, At, B1); PG8_BAR;
;     }
;     E(acc, cur, wr, wc, fr, fq);
;   __device__ __forceinline__ void operator()(const f32x4 (&acc)[2][2][4][2], const pg8::Unit& u, int wr, int wc, int fr, int fq) const {
;     ...
;       float* xo = P->out + (size_t)slice * TS * DM; const u16* x2b = (const u16*)(ws + O_X2B) + (size_t)slice * TS * DM;
; #pragma unroll
;       for (int ai = 0; ai < 2; ++ai) {
;         u32x4 xv[4][2];
; #pragma unroll
;         for (int m = 0; m < 4; ++m)
; #pragma unroll
;           for (int bj = 0; bj < 2; ++bj) xv[m][bj] = *(const u32x4*)(x2b + (size_t)(row0 + ai * 128 + m * 16) * DM + col0 + bj * 128);
	s_waitcnt lgkmcnt(0)
	s_waitcnt lgkmcnt(0)
	v_mfma_f32_16x16x32_bf16 v[94:97], v[130:133], v[146:149], v[94:97]
	v_mfma_f32_16x16x32_bf16 v[90:93], v[138:141], v[146:149], v[90:93]
	v_mfma_f32_16x16x32_bf16 v[86:89], v[130:133], v[154:157], v[86:89]
	v_mfma_f32_16x16x32_bf16 v[82:85], v[138:141], v[154:157], v[82:85]
	v_mfma_f32_16x16x32_bf16 v[76:79], v[130:133], v[174:177], v[76:79]
	v_mfma_f32_16x16x32_bf16 v[72:75], v[138:141], v[174:177], v[72:75]
	v_mfma_f32_16x16x32_bf16 v[68:71], v[130:133], v[182:185], v[68:71]
	v_mfma_f32_16x16x32_bf16 v[64:67], v[138:141], v[182:185], v[64:67]
	v_mfma_f32_16x16x32_bf16 v[94:97], v[134:137], v[150:153], v[94:97]
	v_mfma_f32_16x16x32_bf16 v[90:93], v[142:145], v[150:153], v[90:93]
	v_mfma_f32_16x16x32_bf16 v[86:89], v[134:137], v[158:161], v[86:89]
	v_mfma_f32_16x16x32_bf16 v[82:85], v[142:145], v[158:161], v[82:85]
	v_mfma_f32_16x16x32_bf16 v[76:79], v[134:137], v[178:181], v[76:79]
	v_mfma_f32_16x16x32_bf16 v[72:75], v[142:145], v[178:181], v[72:75]
	v_mfma_f32_16x16x32_bf16 v[68:71], v[134:137], v[190:193], v[68:71]
	v_mfma_f32_16x16x32_bf16 v[64:67], v[142:145], v[190:193], v[64:67]
	s_barrier
	s_add_i32 s10, s10, s14
	v_lshl_add_u64 v[130:131], v[236:237], 0, s[90:91]
	s_mov_b32 m0, s10
	s_nop 0
	global_load_lds_dwordx4 v[130:131], off
	v_lshl_add_u64 v[130:131], v[242:243], 0, s[90:91]
	s_add_i32 m0, s10, 0x2000
	s_nop 0
	global_load_lds_dwordx4 v[130:131], off
	s_waitcnt vmcnt(6)
	s_barrier
	v_mfma_f32_16x16x32_bf16 v[28:31], v[194:197], v[146:149], v[28:31]
	v_mfma_f32_16x16x32_bf16 v[24:27], v[202:205], v[146:149], v[24:27]
	v_mfma_f32_16x16x32_bf16 v[20:23], v[194:197], v[154:157], v[20:23]
	v_mfma_f32_16x16x32_bf16 v[16:19], v[202:205], v[154:157], v[16:19]
	v_mfma_f32_16x16x32_bf16 v[12:15], v[194:197], v[174:177], v[12:15]
	v_mfma_f32_16x16x32_bf16 v[8:11], v[202:205], v[174:177], v[8:11]
	v_mfma_f32_16x16x32_bf16 v[4:7], v[194:197], v[182:185], v[4:7]
	v_mfma_f32_16x16x32_bf16 v[0:3], v[202:205], v[182:185], v[0:3]
	v_mfma_f32_16x16x32_bf16 v[28:31], v[198:201], v[150:153], v[28:31]
	v_mfma_f32_16x16x32_bf16 v[24:27], v[206:209], v[150:153], v[24:27]
	v_mfma_f32_16x16x32_bf16 v[20:23], v[198:201], v[158:161], v[20:23]
	v_mfma_f32_16x16x32_bf16 v[16:19], v[206:209], v[158:161], v[16:19]
	v_mfma_f32_16x16x32_bf16 v[12:15], v[198:201], v[178:181], v[12:15]
	v_mfma_f32_16x16x32_bf16 v[8:11], v[206:209], v[178:181], v[8:11]
	v_mfma_f32_16x16x32_bf16 v[4:7], v[198:201], v[190:193], v[4:7]
	v_mfma_f32_16x16x32_bf16 v[0:3], v[206:209], v[190:193], v[0:3]
	s_add_u32 s74, s74, 0x100
	s_addc_u32 s75, s75, 0
	s_add_u32 s0, s0, 0x100
	s_addc_u32 s1, s1, 0
	s_cmp_ge_u32 s76, s2
	s_mov_b32 s10, s76
	s_barrier
	s_cbranch_scc0 .LBB0_56
	s_cmp_lg_u32 s71, 0
	s_cselect_b64 s[0:1], -1, 0
	s_cmp_eq_u32 s71, 0
	s_cselect_b32 s10, s73, s72
	s_cselect_b32 s11, s72, s73
	s_lshl_b32 s71, s10, 8
	s_add_i32 s71, s71, s28
	v_or_b32_e32 v176, s71, v186
	v_lshl_or_b32 v174, s11, 8, v188
	s_cmp_lt_i32 s98, 2
	s_mov_b64 s[10:11], -1
	s_cbranch_scc1 .LBB0_151
	s_cmp_lt_i32 s98, 4
	s_cbranch_scc1 .LBB0_84
	s_cmp_lt_i32 s98, 5
	s_cbranch_scc1 .LBB0_65
	s_cmp_lg_u32 s98, 5
	s_cbranch_scc0 .LBB0_62
	v_readlane_b32 s10, v254, 18
	v_ashrrev_i32_e32 v175, 31, v174
	v_readlane_b32 s11, v254, 19
	v_ashrrev_i32_e32 v177, 31, v176
	v_lshlrev_b64 v[130:131], 11, v[176:177]
	v_lshl_add_u64 v[136:137], v[174:175], 1, s[10:11]
	v_or_b32_e32 v190, 16, v176
	v_lshl_add_u64 v[130:131], v[136:137], 0, v[130:131]
	v_ashrrev_i32_e32 v191, 31, v190
	flat_load_dwordx4 v[138:141], v[130:131]
	flat_load_dwordx4 v[142:145], v[130:131] offset:256
	v_lshlrev_b64 v[130:131], 11, v[190:191]
	v_or_b32_e32 v192, 32, v176
	v_lshl_add_u64 v[130:131], v[136:137], 0, v[130:131]
	v_ashrrev_i32_e32 v193, 31, v192
	flat_load_dwordx4 v[146:149], v[130:131]
	flat_load_dwordx4 v[150:153], v[130:131] offset:256
	v_lshlrev_b64 v[130:131], 11, v[192:193]
	v_or_b32_e32 v194, 48, v176
	v_lshl_add_u64 v[130:131], v[136:137], 0, v[130:131]
	v_ashrrev_i32_e32 v195, 31, v194
	flat_load_dwordx4 v[154:157], v[130:131]
	flat_load_dwordx4 v[158:161], v[130:131] offset:256
	v_lshlrev_b64 v[130:131], 11, v[194:195]
	v_lshl_add_u64 v[130:131], v[136:137], 0, v[130:131]
	flat_load_dwordx4 v[178:181], v[130:131]
	s_nop 0
	flat_load_dwordx4 v[130:133], v[130:131] offset:256
	v_readlane_b32 s10, v254, 20
	v_readlane_b32 s11, v254, 21
	s_nop 1
	v_lshl_add_u64 v[134:135], v[174:175], 2, s[10:11]
	v_lshlrev_b64 v[182:183], 12, v[176:177]
	v_lshl_add_u64 v[196:197], v[134:135], 0, v[182:183]
	s_waitcnt vmcnt(0) lgkmcnt(0)
; __device__ __forceinline__ float lo16(unsigned v) { return __uint_as_float(v << 16); }
; __device__ __forceinline__ float hi16(unsigned v) { return __uint_as_float(v & 0xffff0000u); }
;   __device__ __forceinline__ void operator()(const f32x4 (&acc)[2][2][4][2], const pg8::Unit& u, int wr, int wc, int fr, int fq) const {
;     ...
;       float* xo = P->out + (size_t)slice * TS * DM; const u16* x2b = (const u16*)(ws + O_X2B) + (size_t)slice * TS * DM;
; #pragma unroll
;       for (int ai = 0; ai < 2; ++ai) {
;         u32x4 xv[4][2];
; #pragma unroll
;         for (int m = 0; m < 4; ++m)
; #pragma unroll
;           for (int bj = 0; bj < 2; ++bj) xv[m][bj] = *(const u32x4*)(x2b + (size_t)(row0 + ai * 128 + m * 16) * DM + col0 + bj * 128);
;         __builtin_amdgcn_sched_barrier(0);
; #pragma unroll
;         for (int m = 0; m < 4; ++m) {
;           const int row = row0 + ai * 128 + m * 16;
; #pragma unroll
;           for (int bj = 0; bj < 2; ++bj) {
;             float* d = xo + (size_t)row * DM + col0 + bj * 128;
;             const u32x4 x4 = xv[m][bj];
;             f32x4 o0 = acc[ai][bj][m][0], o1 = acc[ai][bj][m][1];
;             o0[0] += lo16(x4.x); o0[1] += hi16(x4.x); o0[2] += lo16(x4.y); o0[3] += hi16(x4.y); o1[0] += lo16(x4.z); o1[1] += hi16(x4.z); o1[2] += lo16(x4.w); o1[3] += hi16(x4.w);
;             *(f32x4*)d = o0; *(f32x4*)(d + 4) = o1;
;           }
;         }
	v_lshlrev_b32_e32 v182, 16, v138
	v_and_b32_e32 v183, 0xffff0000, v138
	v_lshlrev_b32_e32 v138, 16, v139
	v_and_b32_e32 v139, 0xffff0000, v139
	v_pk_add_f32 v[184:185], v[128:129], v[138:139]
	v_lshlrev_b32_e32 v138, 16, v140
	v_and_b32_e32 v139, 0xffff0000, v140
	v_lshlrev_b32_e32 v140, 16, v141
	v_and_b32_e32 v141, 0xffff0000, v141
	v_pk_add_f32 v[182:183], v[126:127], v[182:183]
	v_pk_add_f32 v[138:139], v[122:123], v[138:139]
	v_pk_add_f32 v[140:141], v[124:125], v[140:141]
	global_store_dwordx4 v[196:197], v[182:185], off
	global_store_dwordx4 v[196:197], v[138:141], off offset:16
	s_nop 1
	v_lshlrev_b32_e32 v138, 16, v142
	v_and_b32_e32 v139, 0xffff0000, v142
	v_lshlrev_b32_e32 v140, 16, v143
	v_and_b32_e32 v141, 0xffff0000, v143
	v_pk_add_f32 v[138:139], v[60:61], v[138:139]
	v_pk_add_f32 v[140:141], v[62:63], v[140:141]
	v_lshlrev_b32_e32 v142, 16, v144
	v_and_b32_e32 v143, 0xffff0000, v144
	v_lshlrev_b32_e32 v144, 16, v145
	v_and_b32_e32 v145, 0xffff0000, v145
	v_pk_add_f32 v[142:143], v[56:57], v[142:143]
	v_pk_add_f32 v[144:145], v[58:59], v[144:145]
	global_store_dwordx4 v[196:197], v[138:141], off offset:512
	global_store_dwordx4 v[196:197], v[142:145], off offset:528
	s_nop 0
	v_lshlrev_b64 v[138:139], 12, v[190:191]
	v_lshl_add_u64 v[182:183], v[134:135], 0, v[138:139]
	v_lshlrev_b32_e32 v138, 16, v146
	v_and_b32_e32 v139, 0xffff0000, v146
	v_lshlrev_b32_e32 v140, 16, v147
	v_and_b32_e32 v141, 0xffff0000, v147
	v_pk_add_f32 v[138:139], v[118:119], v[138:139]
	v_pk_add_f32 v[140:141], v[120:121], v[140:141]
	v_lshlrev_b32_e32 v142, 16, v148
	v_and_b32_e32 v143, 0xffff0000, v148
	v_lshlrev_b32_e32 v144, 16, v149
	v_and_b32_e32 v145, 0xffff0000, v149
	v_pk_add_f32 v[142:143], v[114:115], v[142:143]
	v_pk_add_f32 v[144:145], v[116:117], v[144:145]
	global_store_dwordx4 v[182:183], v[138:141], off
	global_store_dwordx4 v[182:183], v[142:145], off offset:16
	s_nop 0
	v_lshlrev_b32_e32 v138, 16, v150
	v_and_b32_e32 v139, 0xffff0000, v150
	v_lshlrev_b32_e32 v140, 16, v151
	v_and_b32_e32 v141, 0xffff0000, v151
	v_pk_add_f32 v[138:139], v[52:53], v[138:139]
	v_pk_add_f32 v[140:141], v[54:55], v[140:141]
	v_lshlrev_b32_e32 v142, 16, v152
	v_and_b32_e32 v143, 0xffff0000, v152
	v_lshlrev_b32_e32 v144, 16, v153
	v_and_b32_e32 v145, 0xffff0000, v153
	v_pk_add_f32 v[142:143], v[48:49], v[142:143]
	v_pk_add_f32 v[144:145], v[50:51], v[144:145]
	global_store_dwordx4 v[182:183], v[138:141], off offset:512
	global_store_dwordx4 v[182:183], v[142:145], off offset:528
	s_nop 0
	v_lshlrev_b64 v[138:139], 12, v[192:193]
	v_lshl_add_u64 v[146:147], v[134:135], 0, v[138:139]
	v_lshlrev_b32_e32 v138, 16, v154
	v_and_b32_e32 v139, 0xffff0000, v154
	v_lshlrev_b32_e32 v140, 16, v155
	v_and_b32_e32 v141, 0xffff0000, v155
	v_pk_add_f32 v[138:139], v[110:111], v[138:139]
	v_pk_add_f32 v[140:141], v[112:113], v[140:141]
	v_lshlrev_b32_e32 v142, 16, v156
	v_and_b32_e32 v143, 0xffff0000, v156
	v_lshlrev_b32_e32 v144, 16, v157
	v_and_b32_e32 v145, 0xffff0000, v157
	v_pk_add_f32 v[142:143], v[106:107], v[142:143]
	v_pk_add_f32 v[144:145], v[108:109], v[144:145]
	global_store_dwordx4 v[146:147], v[138:141], off
	global_store_dwordx4 v[146:147], v[142:145], off offset:16
	s_nop 0
	v_lshlrev_b32_e32 v138, 16, v158
	v_and_b32_e32 v139, 0xffff0000, v158
	v_lshlrev_b32_e32 v140, 16, v159
	v_and_b32_e32 v141, 0xffff0000, v159
	v_pk_add_f32 v[138:139], v[44:45], v[138:139]
	v_pk_add_f32 v[140:141], v[46:47], v[140:141]
	v_lshlrev_b32_e32 v142, 16, v160
	v_and_b32_e32 v143, 0xffff0000, v160
	v_lshlrev_b32_e32 v144, 16, v161
	v_and_b32_e32 v145, 0xffff0000, v161
	v_pk_add_f32 v[142:143], v[40:41], v[142:143]
	v_pk_add_f32 v[144:145], v[42:43], v[144:145]
	global_store_dwordx4 v[146:147], v[138:141], off offset:512
	global_store_dwordx4 v[146:147], v[142:145], off offset:528
	s_nop 0
	v_lshlrev_b64 v[138:139], 12, v[194:195]
	v_lshl_add_u64 v[146:147], v[134:135], 0, v[138:139]
	v_lshlrev_b32_e32 v138, 16, v178
	v_and_b32_e32 v139, 0xffff0000, v178
	v_lshlrev_b32_e32 v140, 16, v179
	v_and_b32_e32 v141, 0xffff0000, v179
	v_pk_add_f32 v[138:139], v[102:103], v[138:139]
	v_pk_add_f32 v[140:141], v[104:105], v[140:141]
	v_lshlrev_b32_e32 v142, 16, v180
	v_and_b32_e32 v143, 0xffff0000, v180
	v_lshlrev_b32_e32 v144, 16, v181
	v_and_b32_e32 v145, 0xffff0000, v181
	v_pk_add_f32 v[142:143], v[98:99], v[142:143]
	v_pk_add_f32 v[144:145], v[100:101], v[144:145]
	global_store_dwordx4 v[146:147], v[138:141], off
	global_store_dwordx4 v[146:147], v[142:145], off offset:16
	s_nop 0
	v_lshlrev_b32_e32 v138, 16, v130
	v_and_b32_e32 v139, 0xffff0000, v130
	v_lshlrev_b32_e32 v130, 16, v131
	v_and_b32_e32 v131, 0xffff0000, v131
	v_pk_add_f32 v[138:139], v[36:37], v[138:139]
	v_pk_add_f32 v[140:141], v[38:39], v[130:131]
	v_lshlrev_b32_e32 v130, 16, v132
	v_and_b32_e32 v131, 0xffff0000, v132
	v_lshlrev_b32_e32 v132, 16, v133
	v_and_b32_e32 v133, 0xffff0000, v133
	v_pk_add_f32 v[130:131], v[32:33], v[130:131]
	v_pk_add_f32 v[132:133], v[34:35], v[132:133]
	global_store_dwordx4 v[146:147], v[138:141], off offset:512
	global_store_dwordx4 v[146:147], v[130:133], off offset:528
	v_add_u32_e32 v182, 0x80, v176
	v_ashrrev_i32_e32 v183, 31, v182
	v_lshlrev_b64 v[130:131], 11, v[182:183]
	v_add_u32_e32 v190, 0x90, v176
	v_lshl_add_u64 v[130:131], v[136:137], 0, v[130:131]
	v_ashrrev_i32_e32 v191, 31, v190
	flat_load_dwordx4 v[138:141], v[130:131]
	flat_load_dwordx4 v[142:145], v[130:131] offset:256
	v_lshlrev_b64 v[130:131], 11, v[190:191]
	v_add_u32_e32 v192, 0xa0, v176
	v_lshl_add_u64 v[130:131], v[136:137], 0, v[130:131]
	v_ashrrev_i32_e32 v193, 31, v192
	flat_load_dwordx4 v[146:149], v[130:131]
	flat_load_dwordx4 v[150:153], v[130:131] offset:256
	v_lshlrev_b64 v[130:131], 11, v[192:193]
	v_add_u32_e32 v194, 0xb0, v176
	v_lshl_add_u64 v[130:131], v[136:137], 0, v[130:131]
	v_ashrrev_i32_e32 v195, 31, v194
	flat_load_dwordx4 v[154:157], v[130:131]
	flat_load_dwordx4 v[158:161], v[130:131] offset:256
	v_lshlrev_b64 v[130:131], 11, v[194:195]
	v_lshl_add_u64 v[130:131], v[136:137], 0, v[130:131]
	flat_load_dwordx4 v[178:181], v[130:131]
	s_nop 0
	flat_load_dwordx4 v[130:133], v[130:131] offset:256
	v_lshlrev_b64 v[136:137], 12, v[182:183]
	v_lshl_add_u64 v[196:197], v[134:135], 0, v[136:137]
	s_waitcnt vmcnt(0) lgkmcnt(0)
; __device__ __forceinline__ float lo16(unsigned v) { return __uint_as_float(v << 16); }
; __device__ __forceinline__ float hi16(unsigned v) { return __uint_as_float(v & 0xffff0000u); }
;   __device__ __forceinline__ void operator()(const f32x4 (&acc)[2][2][4][2], const pg8::Unit& u, int wr, int wc, int fr, int fq) const {
;     ...
; #pragma unroll
;         for (int m = 0; m < 4; ++m) {
;           const int row = row0 + ai * 128 + m * 16;
; #pragma unroll
;           for (int bj = 0; bj < 2; ++bj) {
;             float* d = xo + (size_t)row * DM + col0 + bj * 128;
;             const u32x4 x4 = xv[m][bj];
;             f32x4 o0 = acc[ai][bj][m][0], o1 = acc[ai][bj][m][1];
;             o0[0] += lo16(x4.x); o0[1] += hi16(x4.x); o0[2] += lo16(x4.y); o0[3] += hi16(x4.y); o1[0] += lo16(x4.z); o1[1] += hi16(x4.z); o1[2] += lo16(x4.w); o1[3] += hi16(x4.w);
;             *(f32x4*)d = o0; *(f32x4*)(d + 4) = o1;
;           }
;         }
	v_lshlrev_b32_e32 v136, 16, v138
	v_and_b32_e32 v137, 0xffff0000, v138
	v_lshlrev_b32_e32 v138, 16, v139
	v_and_b32_e32 v139, 0xffff0000, v139
	v_pk_add_f32 v[136:137], v[94:95], v[136:137]
	v_pk_add_f32 v[138:139], v[96:97], v[138:139]
	v_lshlrev_b32_e32 v182, 16, v140
	v_and_b32_e32 v183, 0xffff0000, v140
	v_lshlrev_b32_e32 v140, 16, v141
	v_and_b32_e32 v141, 0xffff0000, v141
	v_pk_add_f32 v[182:183], v[90:91], v[182:183]
	v_pk_add_f32 v[184:185], v[92:93], v[140:141]
	global_store_dwordx4 v[196:197], v[136:139], off
	global_store_dwordx4 v[196:197], v[182:185], off offset:16
	v_lshlrev_b32_e32 v140, 16, v144
	v_lshlrev_b32_e32 v136, 16, v142
	v_and_b32_e32 v137, 0xffff0000, v142
	v_lshlrev_b32_e32 v138, 16, v143
	v_and_b32_e32 v139, 0xffff0000, v143
	v_pk_add_f32 v[136:137], v[28:29], v[136:137]
	v_pk_add_f32 v[138:139], v[30:31], v[138:139]
	v_and_b32_e32 v141, 0xffff0000, v144
	v_lshlrev_b32_e32 v142, 16, v145
	v_and_b32_e32 v143, 0xffff0000, v145
	v_pk_add_f32 v[140:141], v[24:25], v[140:141]
	v_pk_add_f32 v[142:143], v[26:27], v[142:143]
	global_store_dwordx4 v[196:197], v[136:139], off offset:512
	global_store_dwordx4 v[196:197], v[140:143], off offset:528
	s_nop 0
	v_lshlrev_b64 v[136:137], 12, v[190:191]
	v_lshl_add_u64 v[144:145], v[134:135], 0, v[136:137]
	v_lshlrev_b32_e32 v136, 16, v146
	v_and_b32_e32 v137, 0xffff0000, v146
	v_lshlrev_b32_e32 v138, 16, v147
	v_and_b32_e32 v139, 0xffff0000, v147
	v_pk_add_f32 v[136:137], v[86:87], v[136:137]
	v_pk_add_f32 v[138:139], v[88:89], v[138:139]
	v_lshlrev_b32_e32 v140, 16, v148
	v_and_b32_e32 v141, 0xffff0000, v148
	v_lshlrev_b32_e32 v142, 16, v149
	v_and_b32_e32 v143, 0xffff0000, v149
	v_pk_add_f32 v[140:141], v[82:83], v[140:141]
	v_pk_add_f32 v[142:143], v[84:85], v[142:143]
	global_store_dwordx4 v[144:145], v[136:139], off
	global_store_dwordx4 v[144:145], v[140:143], off offset:16
	s_nop 0
	v_lshlrev_b32_e32 v136, 16, v150
	v_and_b32_e32 v137, 0xffff0000, v150
	v_lshlrev_b32_e32 v138, 16, v151
	v_and_b32_e32 v139, 0xffff0000, v151
	v_pk_add_f32 v[136:137], v[20:21], v[136:137]
	v_pk_add_f32 v[138:139], v[22:23], v[138:139]
	v_lshlrev_b32_e32 v140, 16, v152
	v_and_b32_e32 v141, 0xffff0000, v152
	v_lshlrev_b32_e32 v142, 16, v153
	v_and_b32_e32 v143, 0xffff0000, v153
	v_pk_add_f32 v[140:141], v[16:17], v[140:141]
	v_pk_add_f32 v[142:143], v[18:19], v[142:143]
	global_store_dwordx4 v[144:145], v[136:139], off offset:512
	global_store_dwordx4 v[144:145], v[140:143], off offset:528
	s_nop 0
	v_lshlrev_b64 v[136:137], 12, v[192:193]
	v_lshl_add_u64 v[144:145], v[134:135], 0, v[136:137]
	v_lshlrev_b32_e32 v136, 16, v154
	v_and_b32_e32 v137, 0xffff0000, v154
	v_lshlrev_b32_e32 v138, 16, v155
	v_and_b32_e32 v139, 0xffff0000, v155
	v_pk_add_f32 v[136:137], v[76:77], v[136:137]
	v_pk_add_f32 v[138:139], v[78:79], v[138:139]
	v_lshlrev_b32_e32 v140, 16, v156
	v_and_b32_e32 v141, 0xffff0000, v156
	v_lshlrev_b32_e32 v142, 16, v157
	v_and_b32_e32 v143, 0xffff0000, v157
	v_pk_add_f32 v[140:141], v[72:73], v[140:141]
	v_pk_add_f32 v[142:143], v[74:75], v[142:143]
	global_store_dwordx4 v[144:145], v[136:139], off
	global_store_dwordx4 v[144:145], v[140:143], off offset:16
	s_nop 0
	v_lshlrev_b32_e32 v136, 16, v158
	v_and_b32_e32 v137, 0xffff0000, v158
	v_lshlrev_b32_e32 v138, 16, v159
	v_and_b32_e32 v139, 0xffff0000, v159
	v_pk_add_f32 v[136:137], v[12:13], v[136:137]
	v_pk_add_f32 v[138:139], v[14:15], v[138:139]
	v_lshlrev_b32_e32 v140, 16, v160
	v_and_b32_e32 v141, 0xffff0000, v160
	v_lshlrev_b32_e32 v142, 16, v161
	v_and_b32_e32 v143, 0xffff0000, v161
	v_pk_add_f32 v[140:141], v[8:9], v[140:141]
	v_pk_add_f32 v[142:143], v[10:11], v[142:143]
	global_store_dwordx4 v[144:145], v[136:139], off offset:512
	global_store_dwordx4 v[144:145], v[140:143], off offset:528
	s_nop 0
	v_lshlrev_b64 v[136:137], 12, v[194:195]
	v_lshl_add_u64 v[142:143], v[134:135], 0, v[136:137]
	v_lshlrev_b32_e32 v134, 16, v178
	v_and_b32_e32 v135, 0xffff0000, v178
	v_lshlrev_b32_e32 v136, 16, v179
	v_and_b32_e32 v137, 0xffff0000, v179
	v_pk_add_f32 v[134:135], v[68:69], v[134:135]
	v_pk_add_f32 v[136:137], v[70:71], v[136:137]
	v_lshlrev_b32_e32 v138, 16, v180
	v_and_b32_e32 v139, 0xffff0000, v180
	v_lshlrev_b32_e32 v140, 16, v181
	v_and_b32_e32 v141, 0xffff0000, v181
	v_pk_add_f32 v[138:139], v[64:65], v[138:139]
	v_pk_add_f32 v[140:141], v[66:67], v[140:141]
	global_store_dwordx4 v[142:143], v[134:137], off
	global_store_dwordx4 v[142:143], v[138:141], off offset:16
	s_nop 0
	v_lshlrev_b32_e32 v134, 16, v130
	v_and_b32_e32 v135, 0xffff0000, v130
	v_lshlrev_b32_e32 v130, 16, v131
	v_and_b32_e32 v131, 0xffff0000, v131
	v_pk_add_f32 v[134:135], v[4:5], v[134:135]
	v_pk_add_f32 v[136:137], v[6:7], v[130:131]
	v_lshlrev_b32_e32 v130, 16, v132
	v_and_b32_e32 v131, 0xffff0000, v132
	v_lshlrev_b32_e32 v132, 16, v133
	v_and_b32_e32 v133, 0xffff0000, v133
	v_pk_add_f32 v[130:131], v[0:1], v[130:131]
	v_pk_add_f32 v[132:133], v[2:3], v[132:133]
	global_store_dwordx4 v[142:143], v[134:137], off offset:512
	global_store_dwordx4 v[142:143], v[130:133], off offset:528
	s_mov_b64 s[10:11], 0
